# diff-attention loop: tile t+2 K/V LDS-DMA issue moved from the tile head into the QK MFMA shadow, list byte prefetched at loop top
# baseline (speedup 1.0000x reference)
;     __device__ __forceinline__ int k_row(int t, int j) const { return (kr_lo + t) * 64 + j; }
; template <int KSTEPS, class Pol>
; __device__ __forceinline__ void attn_pass(LAS unsigned char* lds, const Pol& P, const bf16_t* qb, int ldq, const bf16_t* kb, int ldk, const bf16_t* vb, int ldv,
;                                           float qs, f32x16 (&O)[4], float& m, float& l) {
;     ...
;     auto dma = [&](int t, int st) __attribute__((always_inline)) {
;         const unsigned sbase = (unsigned)(size_t)lds + (unsigned)(st * A_STAGE);
; #pragma unroll
;         for (int j = 0; j < NKI; ++j) {
;             const int inst = wave * NKI + j;
;             if (KSTEPS == 8) { const int row = inst * 4 + (lane >> 4), slot = lane & 15, c = slot ^ (row & 15);
;                 dma16(kb + (size_t)P.k_row(t, row) * ldk + c * 8, sbase + inst * 1024);
;             } else { const int row = inst * 8 + (lane >> 3), slot = lane & 7, c = slot ^ ((row >> 1) & 7);
;                 dma16(kb + (size_t)P.k_row(t, row) * ldk + c * 8, sbase + inst * 1024); }
;         }
; #pragma unroll
;         for (int j = 0; j < 2; ++j) {
;             const int inst = wave * 2 + j, row = inst * 4 + (lane >> 4), slot = lane & 15, c = slot ^ (((row & 3) << 2) | ((row >> 2) & 3));
;             dma16(vb + (size_t)P.k_row(t, row) * ldv + c * 8, sbase + 16384 + inst * 1024);
;         }
;     ...
;     for (int t = 0; t < nt; ++t) {
;         const int st2 = (st >= 1) ? st - 1 : 2;
;         if (t + 2 < nt) dma(t + 2, st2);
.LBB0_497:
	s_add_i32 s98, s48, 0x18800
	v_mov_b32_e32 v202, s98
	ds_read_u8 v202, v202
	s_add_i32 s98, s48, 0x18802
	v_mov_b32_e32 v201, s98
	ds_read_u8 v201, v201
	s_add_i32 s36, s48, 2
	s_cmp_ge_i32 s36, s44
	s_cselect_b64 s[2:3], -1, 0
	s_lshl_b32 s51, s49, 15

; #define LAS __attribute__((address_space(3)))
; #define MFMA32(a, b, c) __builtin_amdgcn_mfma_f32_32x32x16_bf16((a), (b), (c), 0, 0, 0)
;     __device__ __forceinline__ int k_row(int t, int j) const { return (kr_lo + t) * 64 + j; }
; template <int KSTEPS, class Pol>
; __device__ __forceinline__ void attn_pass(LAS unsigned char* lds, const Pol& P, const bf16_t* qb, int ldq, const bf16_t* kb, int ldk, const bf16_t* vb, int ldv,
;                                           float qs, f32x16 (&O)[4], float& m, float& l) {
;     ...
;     auto dma = [&](int t, int st) __attribute__((always_inline)) {
;         const unsigned sbase = (unsigned)(size_t)lds + (unsigned)(st * A_STAGE);
; #pragma unroll
;         for (int j = 0; j < NKI; ++j) {
;             const int inst = wave * NKI + j;
;             if (KSTEPS == 8) { const int row = inst * 4 + (lane >> 4), slot = lane & 15, c = slot ^ (row & 15);
;                 dma16(kb + (size_t)P.k_row(t, row) * ldk + c * 8, sbase + inst * 1024);
;             } else { const int row = inst * 8 + (lane >> 3), slot = lane & 7, c = slot ^ ((row >> 1) & 7);
;                 dma16(kb + (size_t)P.k_row(t, row) * ldk + c * 8, sbase + inst * 1024); }
;         }
; #pragma unroll
;         for (int j = 0; j < 2; ++j) {
;             const int inst = wave * 2 + j, row = inst * 4 + (lane >> 4), slot = lane & 15, c = slot ^ (((row & 3) << 2) | ((row >> 2) & 3));
;             dma16(vb + (size_t)P.k_row(t, row) * ldv + c * 8, sbase + 16384 + inst * 1024);
;         }
;     ...
;         LAS unsigned char* Kb = lds + st * A_STAGE + krow;
;         f32x16 S0, S1;
;         P.fill(S0, S1, qi, half, t, wave);
; #pragma unroll
;         for (int ks = 0; ks < KSTEPS; ++ks) {
;             const int so = ((2 * ks) ^ kx) << 4;
;             const bf16x8 a0 = *(const LAS bf16x8*)(Kb + so);
;             const bf16x8 a1 = *(const LAS bf16x8*)(Kb + 32 * KROWB + so);
;             S0 = MFMA32(a0, qf[ks], S0);
;             S1 = MFMA32(a1, qf[ks], S1);
;         }
;         S0 = S0 * qs; S1 = S1 * qs;
;         float mx = fmaxf(S0[0], S1[0]);
; #pragma unroll
;         for (int i = 1; i < 16; ++i) mx = fmaxf(fmaxf(mx, S0[i]), S1[i]);
;         mx = fmaxf(mx, __shfl_xor(mx, 32));
;         const float mnew = fmaxf(m, mx);
;         const float alpha = __builtin_amdgcn_exp2f(m - mnew);
;         m = mnew;
.LBB0_505:
	s_add_i32 s36, s51, 0
	v_add_u32_e32 v0, s36, v151
	v_add_u32_e32 v6, v0, v152
	ds_read_b128 v[2:5], v6
	ds_read_b128 v[6:9], v6 offset:4096
	v_add_u32_e32 v200, v0, v153
	ds_read_b128 v[192:195], v200
	ds_read_b128 v[196:199], v200 offset:4096
	s_mov_b32 s40, 0x3e38aa3b
	s_waitcnt lgkmcnt(3)
	v_mfma_f32_32x32x16_bf16 v[80:95], v[2:5], v[112:115], v[80:95]
	s_waitcnt lgkmcnt(2)
	v_mfma_f32_32x32x16_bf16 v[96:111], v[6:9], v[112:115], v[96:111]
	v_add_u32_e32 v6, v0, v155
	ds_read_b128 v[2:5], v6
	ds_read_b128 v[6:9], v6 offset:4096
	s_add_i32 s100, s48, 2
	s_cmp_ge_i32 s100, s44
	s_cbranch_scc1 .Ldiff_nodma
	s_add_i32 s98, s51, 0xffff8000
	s_cmp_gt_i32 s49, 0
	s_cselect_b32 s99, s98, 0x10000
	v_lshl_add_u32 v208, v201, 6, v129
	v_mad_i64_i32 v[204:205], s[100:101], v208, s67, v[132:133]
	s_add_i32 s98, s99, s42
	s_mov_b32 m0, s98
	s_nop 0
	global_load_lds_dwordx4 v[204:205], off
	s_add_i32 s99, s99, 0x4000
	v_lshl_add_u32 v208, v201, 6, v130
	v_mad_i64_i32 v[210:211], s[100:101], v208, s67, v[134:135]
	s_add_i32 s98, s99, s43
	s_mov_b32 m0, s98
	s_nop 0
	global_load_lds_dwordx4 v[210:211], off
	s_add_i32 s99, s99, s45
	v_lshl_add_u32 v208, v201, 6, v149
	v_mad_i64_i32 v[212:213], s[100:101], v208, s67, v[136:137]
	s_mov_b32 m0, s99
	s_nop 0
	global_load_lds_dwordx4 v[212:213], off
.Ldiff_nodma:
	s_waitcnt lgkmcnt(3)
	v_mfma_f32_32x32x16_bf16 v[80:95], v[192:195], v[116:119], v[80:95]
	s_waitcnt lgkmcnt(2)
	v_mfma_f32_32x32x16_bf16 v[96:111], v[196:199], v[116:119], v[96:111]
	v_add_u32_e32 v200, v0, v156
	ds_read_b128 v[192:195], v200
	ds_read_b128 v[196:199], v200 offset:4096
	s_waitcnt lgkmcnt(3)
	v_mfma_f32_32x32x16_bf16 v[80:95], v[2:5], v[120:123], v[80:95]
	s_waitcnt lgkmcnt(2)
	v_mfma_f32_32x32x16_bf16 v[96:111], v[6:9], v[120:123], v[96:111]
	s_waitcnt lgkmcnt(1)
	v_mfma_f32_32x32x16_bf16 v[80:95], v[192:195], v[124:127], v[80:95]
	s_waitcnt lgkmcnt(0)
	v_mfma_f32_32x32x16_bf16 v[96:111], v[196:199], v[124:127], v[96:111]
	v_add_u32_e32 v7, s36, v158
	v_add_u32_e32 v139, s36, v159
	v_add_u32_e32 v142, s36, v160
	v_add_u32_e32 v143, s36, v161
	v_add_u32_e32 v146, s36, v162
	v_add_u32_e32 v147, s36, v163
	v_add_u32_e32 v169, s36, v164
	v_add_u32_e32 v170, s36, v165
	ds_read_b64_tr_b16 v[176:177], v7 offset:16384
	ds_read_b64_tr_b16 v[178:179], v139 offset:2048
	ds_read_b64_tr_b16 v[180:181], v142 offset:16384
	ds_read_b64_tr_b16 v[182:183], v143 offset:2048
	ds_read_b64_tr_b16 v[192:193], v146 offset:16384
	ds_read_b64_tr_b16 v[194:195], v147 offset:2048
	ds_read_b64_tr_b16 v[196:197], v169 offset:16384
	ds_read_b64_tr_b16 v[198:199], v170 offset:2048
	v_max_f32_e32 v0, v80, v96
	v_max3_f32 v0, v0, v81, v97
	v_max3_f32 v0, v0, v82, v98
	v_max3_f32 v0, v0, v83, v99
	v_max3_f32 v0, v0, v84, v100
	v_max3_f32 v0, v0, v85, v101
	v_max3_f32 v0, v0, v86, v102
	v_max3_f32 v0, v0, v87, v103
	v_max3_f32 v0, v0, v88, v104
	v_max3_f32 v0, v0, v89, v105
	v_max3_f32 v0, v0, v90, v106
	v_max3_f32 v0, v0, v91, v107
	v_max3_f32 v0, v0, v92, v108
	v_max3_f32 v0, v0, v93, v109
	v_max3_f32 v0, v0, v94, v110
	v_max3_f32 v0, v0, v95, v111
	v_mul_f32_e64 v0, v0, s40
	ds_bpermute_b32 v6, v148, v0
	s_waitcnt lgkmcnt(0)
	v_max3_f32 v0, v167, v0, v6
	v_sub_f32_e32 v6, v167, v0
	v_exp_f32_e32 v6, v6
	s_nop 0
	v_cmp_neq_f32_e32 vcc, 1.0, v6
	s_cbranch_vccz .LBB0_507
	v_pk_mul_f32 v[78:79], v[78:79], v[6:7] op_sel_hi:[1,0]
	v_pk_mul_f32 v[76:77], v[76:77], v[6:7] op_sel_hi:[1,0]
	v_pk_mul_f32 v[74:75], v[74:75], v[6:7] op_sel_hi:[1,0]
	v_pk_mul_f32 v[72:73], v[72:73], v[6:7] op_sel_hi:[1,0]
	v_pk_mul_f32 v[70:71], v[70:71], v[6:7] op_sel_hi:[1,0]
	v_pk_mul_f32 v[68:69], v[68:69], v[6:7] op_sel_hi:[1,0]
	v_pk_mul_f32 v[66:67], v[66:67], v[6:7] op_sel_hi:[1,0]
	v_pk_mul_f32 v[64:65], v[64:65], v[6:7] op_sel_hi:[1,0]
	v_pk_mul_f32 v[62:63], v[62:63], v[6:7] op_sel_hi:[1,0]
	v_pk_mul_f32 v[60:61], v[60:61], v[6:7] op_sel_hi:[1,0]
	v_pk_mul_f32 v[58:59], v[58:59], v[6:7] op_sel_hi:[1,0]
	v_pk_mul_f32 v[56:57], v[56:57], v[6:7] op_sel_hi:[1,0]
	v_pk_mul_f32 v[54:55], v[54:55], v[6:7] op_sel_hi:[1,0]
	v_pk_mul_f32 v[52:53], v[52:53], v[6:7] op_sel_hi:[1,0]
	v_pk_mul_f32 v[50:51], v[50:51], v[6:7] op_sel_hi:[1,0]
	v_pk_mul_f32 v[48:49], v[48:49], v[6:7] op_sel_hi:[1,0]
	v_pk_mul_f32 v[46:47], v[46:47], v[6:7] op_sel_hi:[1,0]
	v_pk_mul_f32 v[44:45], v[44:45], v[6:7] op_sel_hi:[1,0]
	v_pk_mul_f32 v[42:43], v[42:43], v[6:7] op_sel_hi:[1,0]
	v_pk_mul_f32 v[40:41], v[40:41], v[6:7] op_sel_hi:[1,0]
	v_pk_mul_f32 v[38:39], v[38:39], v[6:7] op_sel_hi:[1,0]
	v_pk_mul_f32 v[36:37], v[36:37], v[6:7] op_sel_hi:[1,0]
	v_pk_mul_f32 v[34:35], v[34:35], v[6:7] op_sel_hi:[1,0]
	v_pk_mul_f32 v[32:33], v[32:33], v[6:7] op_sel_hi:[1,0]
	v_pk_mul_f32 v[30:31], v[30:31], v[6:7] op_sel_hi:[1,0]
	v_pk_mul_f32 v[28:29], v[28:29], v[6:7] op_sel_hi:[1,0]
	v_pk_mul_f32 v[26:27], v[26:27], v[6:7] op_sel_hi:[1,0]
	v_pk_mul_f32 v[24:25], v[24:25], v[6:7] op_sel_hi:[1,0]
	v_pk_mul_f32 v[22:23], v[22:23], v[6:7] op_sel_hi:[1,0]
	v_pk_mul_f32 v[20:21], v[20:21], v[6:7] op_sel_hi:[1,0]
	v_pk_mul_f32 v[18:19], v[18:19], v[6:7] op_sel_hi:[1,0]
	v_pk_mul_f32 v[16:17], v[16:17], v[6:7] op_sel_hi:[1,0]
